# compress-bias loop in phase 1: 16 loads in flight per iteration instead of 1 (same fp32 order)
# speedup vs baseline: 1.0488x; 1.0333x over previous
.LBB0_277:
	s_mov_b64 s[8:9], 0x1000
	global_load_dword v22, v[0:1], off
	global_load_dword v23, v[0:1], off offset:4
	global_load_dword v24, v[0:1], off offset:8
	global_load_dword v25, v[0:1], off offset:12
	global_load_dword v26, v[0:1], off offset:16
	global_load_dword v27, v[0:1], off offset:20
	global_load_dword v28, v[0:1], off offset:24
	global_load_dword v29, v[0:1], off offset:28
	global_load_dword v30, v[0:1], off offset:32
	global_load_dword v31, v[0:1], off offset:36
	global_load_dword v32, v[0:1], off offset:40
	global_load_dword v33, v[0:1], off offset:44
	global_load_dword v34, v[0:1], off offset:48
	global_load_dword v35, v[0:1], off offset:52
	global_load_dword v36, v[0:1], off offset:56
	global_load_dword v37, v[0:1], off offset:60
	global_load_dword v38, v[2:3], off
	global_load_dword v39, v[2:3], off offset:1024
	global_load_dword v40, v[2:3], off offset:2048
	global_load_dword v41, v[2:3], off offset:3072
	v_lshl_add_u64 v[2:3], v[2:3], 0, s[8:9]
	global_load_dword v42, v[2:3], off
	global_load_dword v43, v[2:3], off offset:1024
	global_load_dword v44, v[2:3], off offset:2048
	global_load_dword v45, v[2:3], off offset:3072
	v_lshl_add_u64 v[2:3], v[2:3], 0, s[8:9]
	global_load_dword v46, v[2:3], off
	global_load_dword v47, v[2:3], off offset:1024
	global_load_dword v48, v[2:3], off offset:2048
	global_load_dword v49, v[2:3], off offset:3072
	v_lshl_add_u64 v[2:3], v[2:3], 0, s[8:9]
	global_load_dword v50, v[2:3], off
	global_load_dword v51, v[2:3], off offset:1024
	global_load_dword v52, v[2:3], off offset:2048
	global_load_dword v53, v[2:3], off offset:3072
	v_lshl_add_u64 v[2:3], v[2:3], 0, s[8:9]
	v_add_u32_e32 v7, 16, v7
	v_cmp_ge_i32_e32 vcc, v7, v6
	v_lshl_add_u64 v[0:1], v[0:1], 0, 64
	s_nop 1
	s_or_b64 s[6:7], vcc, s[6:7]
	s_waitcnt vmcnt(0)
	v_fmac_f32_e32 v8, v22, v38
	v_fmac_f32_e32 v8, v23, v39
	v_fmac_f32_e32 v8, v24, v40
	v_fmac_f32_e32 v8, v25, v41
	v_fmac_f32_e32 v8, v26, v42
	v_fmac_f32_e32 v8, v27, v43
	v_fmac_f32_e32 v8, v28, v44
	v_fmac_f32_e32 v8, v29, v45
	v_fmac_f32_e32 v8, v30, v46
	v_fmac_f32_e32 v8, v31, v47
	v_fmac_f32_e32 v8, v32, v48
	v_fmac_f32_e32 v8, v33, v49
	v_fmac_f32_e32 v8, v34, v50
	v_fmac_f32_e32 v8, v35, v51
	v_fmac_f32_e32 v8, v36, v52
	v_fmac_f32_e32 v8, v37, v53
	s_andn2_b64 exec, exec, s[6:7]
	s_cbranch_execnz .LBB0_277
	s_or_b64 exec, exec, s[6:7]
	v_lshlrev_b32_e32 v0, 2, v20
	v_cmp_gt_i32_e32 vcc, 32, v20
	ds_write_b32 v0, v8
	s_waitcnt lgkmcnt(0)
	s_barrier
	s_and_saveexec_b64 s[6:7], vcc
	s_cbranch_execz .LBB0_280
	ds_read2_b32 v[2:3], v0 offset1:32
	v_readlane_b32 s5, v251, 46
	s_waitcnt lgkmcnt(0)
	v_add_f32_e32 v1, 0, v2
	v_add_f32_e32 v1, v1, v3
	ds_read2_b32 v[2:3], v0 offset0:64 offset1:96
	s_waitcnt lgkmcnt(0)
	v_add_f32_e32 v1, v1, v2
	v_add_f32_e32 v1, v1, v3
	ds_read2_b32 v[2:3], v0 offset0:128 offset1:160
	s_waitcnt lgkmcnt(0)
	v_add_f32_e32 v1, v1, v2
	v_add_f32_e32 v2, v1, v3
	ds_read2_b32 v[0:1], v0 offset0:192 offset1:224
	s_waitcnt lgkmcnt(0)
	v_add_f32_e32 v0, v2, v0
	v_add_f32_e32 v2, v0, v1
	v_add_u32_e32 v0, s5, v20
	v_ashrrev_i32_e32 v1, 31, v0
	v_lshl_add_u64 v[0:1], v[0:1], 2, s[0:1]
	v_add_co_u32_e32 v0, vcc, 0xe280000, v0
	s_nop 1
	v_addc_co_u32_e32 v1, vcc, 0, v1, vcc
	global_store_dword v[0:1], v2, off
